# Up-proj epilogue: conv-weight loads waited once before the first row block; removed 16 per-row vmcnt waits that only waited for the previous row's store
# speedup vs baseline: 1.0096x; 1.0038x over previous
; #define LAS __attribute__((address_space(3)))
; __device__ __forceinline__ float dpp_ror1(float v) { return __builtin_bit_cast(float, __builtin_amdgcn_mov_dpp(__builtin_bit_cast(int, v), 0x121, 0xf, 0xf, true)); }
; __device__ __forceinline__ float dpp_ror2(float v) { return __builtin_bit_cast(float, __builtin_amdgcn_mov_dpp(__builtin_bit_cast(int, v), 0x122, 0xf, 0xf, true)); }
;     __device__ __forceinline__ void operator()(AccT& acc, const Unit& u, int wr, int wc, int fr, int fq, LAS unsigned char* ldsx) const {
;     ...
;         for (int ai = 0; ai < 2; ++ai) {
;             const int s = ai * 2 + wr;
;             f32x4 pg[2], pv[2];
; #pragma unroll
;             for (int n = 0; n < 2; ++n) { pg[n] = (f32x4){0.f, 0.f, 0.f, 0.f}; pv[n] = pg[n]; }
;             if (s > 0 && fr >= 14) {
; #pragma unroll
;                 for (int n = 0; n < 2; ++n) { const LAS float* q = xch + (((s - 1) * 2 + (fr - 14)) * 256 + wc * 32 + n * 16 + 4 * fq); pg[n] = *(const LAS f32x4*)q; pv[n] = *(const LAS f32x4*)(q + 128); }
;             }
; #pragma unroll
;             for (int m = 0; m < 4; ++m) {
;                 u32x4 w;
; #pragma unroll
;                 for (int n = 0; n < 2; ++n) {
;                     const f32x4 cg = acc[ai][0][m][n], cv = acc[ai][1][m][n]; f32x4 o;
;                     float og[4];
;                     { float s1[4], s2[4];
; #pragma unroll
;                       for (int i = 0; i < 4; ++i) { s1[i] = hi1 ? pg[n][i] : cg[i]; s2[i] = hi2 ? pg[n][i] : cg[i]; }
; #pragma unroll
;                       for (int i = 0; i < 4; ++i) { s1[i] = dpp_ror1(s1[i]); s2[i] = dpp_ror2(s2[i]); }
; #pragma unroll
;                       for (int i = 0; i < 4; ++i) og[i] = wg[n][2][i] * cg[i] + wg[n][1][i] * s1[i] + wg[n][0][i] * s2[i]; }
.LBB0_118:
	s_or_b64 exec, exec, s[0:1]
	v_pk_mul_f32 v[158:159], v[158:159], v[230:231] op_sel_hi:[1,0]
	v_cmp_eq_u32_e64 s[42:43], 15, v212
	v_pk_mul_f32 v[160:161], v[160:161], v[230:231] op_sel_hi:[1,0]
	v_pk_mul_f32 v[150:151], v[150:151], v[230:231] op_sel_hi:[1,0]
	s_waitcnt lgkmcnt(3)
	v_cndmask_b32_e64 v200, v158, v190, s[42:43]
	v_cndmask_b32_e64 v190, v158, v190, s[40:41]
	v_cndmask_b32_e64 v201, v159, v191, s[42:43]
	v_cndmask_b32_e64 v191, v159, v191, s[40:41]
	v_pk_mul_f32 v[156:157], v[156:157], v[230:231] op_sel_hi:[1,0]
	v_pk_mul_f32 v[154:155], v[154:155], v[230:231] op_sel_hi:[1,0]
	v_pk_mul_f32 v[152:153], v[152:153], v[230:231] op_sel_hi:[1,0]
	v_cndmask_b32_e64 v202, v160, v192, s[42:43]
	v_cndmask_b32_e64 v192, v160, v192, s[40:41]
	v_cndmask_b32_e64 v203, v161, v193, s[42:43]
	v_cndmask_b32_e64 v193, v161, v193, s[40:41]
	v_mov_b32_dpp v240, v190 row_ror:2 row_mask:0xf bank_mask:0xf bound_ctrl:1
	v_mov_b32_dpp v241, v191 row_ror:2 row_mask:0xf bank_mask:0xf bound_ctrl:1
	s_waitcnt lgkmcnt(1)
	v_cndmask_b32_e64 v190, v150, v186, s[42:43]
	v_cndmask_b32_e64 v186, v150, v186, s[40:41]
	v_cndmask_b32_e64 v191, v151, v187, s[42:43]
	v_cndmask_b32_e64 v187, v151, v187, s[40:41]
	v_add_u32_e32 v204, s82, v212
	v_pk_mul_f32 v[148:149], v[148:149], v[230:231] op_sel_hi:[1,0]
	v_pk_mul_f32 v[146:147], v[146:147], v[230:231] op_sel_hi:[1,0]
	v_mov_b32_dpp v244, v200 row_ror:1 row_mask:0xf bank_mask:0xf bound_ctrl:1
	v_mov_b32_dpp v245, v201 row_ror:1 row_mask:0xf bank_mask:0xf bound_ctrl:1
	v_mov_b32_dpp v230, v192 row_ror:2 row_mask:0xf bank_mask:0xf bound_ctrl:1
	v_mov_b32_dpp v231, v193 row_ror:2 row_mask:0xf bank_mask:0xf bound_ctrl:1
	v_cndmask_b32_e64 v192, v152, v188, s[42:43]
	v_cndmask_b32_e64 v193, v153, v189, s[42:43]
	v_cndmask_b32_e64 v189, v153, v189, s[40:41]
	v_mov_b32_dpp v242, v186 row_ror:2 row_mask:0xf bank_mask:0xf bound_ctrl:1
	v_mov_b32_dpp v243, v187 row_ror:2 row_mask:0xf bank_mask:0xf bound_ctrl:1
	v_cndmask_b32_e64 v186, v154, v182, s[42:43]
	v_cndmask_b32_e64 v187, v155, v183, s[42:43]
	v_cndmask_b32_e64 v183, v155, v183, s[40:41]
	v_cndmask_b32_e64 v200, v157, v185, s[42:43]
	v_cndmask_b32_e64 v201, v157, v185, s[40:41]
	v_cndmask_b32_e64 v188, v152, v188, s[40:41]
	v_mov_b32_dpp v238, v190 row_ror:1 row_mask:0xf bank_mask:0xf bound_ctrl:1
	v_mov_b32_dpp v239, v191 row_ror:1 row_mask:0xf bank_mask:0xf bound_ctrl:1
	v_mov_b32_dpp v234, v192 row_ror:1 row_mask:0xf bank_mask:0xf bound_ctrl:1
	v_mov_b32_dpp v235, v193 row_ror:1 row_mask:0xf bank_mask:0xf bound_ctrl:1
	v_mov_b32_dpp v237, v189 row_ror:2 row_mask:0xf bank_mask:0xf bound_ctrl:1
	v_cndmask_b32_e64 v182, v154, v182, s[40:41]
	v_cndmask_b32_e64 v190, v156, v184, s[42:43]
	v_cndmask_b32_e64 v191, v156, v184, s[40:41]
	v_mov_b32_dpp v192, v186 row_ror:1 row_mask:0xf bank_mask:0xf bound_ctrl:1
	v_mov_b32_dpp v193, v187 row_ror:1 row_mask:0xf bank_mask:0xf bound_ctrl:1
	v_mov_b32_dpp v189, v183 row_ror:2 row_mask:0xf bank_mask:0xf bound_ctrl:1
	v_mov_b32_dpp v185, v200 row_ror:1 row_mask:0xf bank_mask:0xf bound_ctrl:1
	v_mov_b32_dpp v183, v201 row_ror:2 row_mask:0xf bank_mask:0xf bound_ctrl:1
	s_waitcnt lgkmcnt(0)
	v_cndmask_b32_e64 v186, v146, v178, s[42:43]
	v_cndmask_b32_e64 v178, v146, v178, s[40:41]
	v_cndmask_b32_e64 v187, v147, v179, s[42:43]
	v_cndmask_b32_e64 v179, v147, v179, s[40:41]
	v_cndmask_b32_e64 v200, v148, v180, s[42:43]
	v_cndmask_b32_e64 v180, v148, v180, s[40:41]
	v_cndmask_b32_e64 v201, v149, v181, s[42:43]
	v_cndmask_b32_e64 v181, v149, v181, s[40:41]
	v_cmp_gt_i32_e32 vcc, 2, v204
	s_xor_b64 s[0:1], s[16:17], -1
	v_mov_b32_dpp v232, v202 row_ror:1 row_mask:0xf bank_mask:0xf bound_ctrl:1
	v_mov_b32_dpp v233, v203 row_ror:1 row_mask:0xf bank_mask:0xf bound_ctrl:1
	v_mov_b32_dpp v236, v188 row_ror:2 row_mask:0xf bank_mask:0xf bound_ctrl:1
	v_mov_b32_dpp v188, v182 row_ror:2 row_mask:0xf bank_mask:0xf bound_ctrl:1
	v_mov_b32_dpp v184, v190 row_ror:1 row_mask:0xf bank_mask:0xf bound_ctrl:1
	v_mov_b32_dpp v182, v191 row_ror:2 row_mask:0xf bank_mask:0xf bound_ctrl:1
	v_mov_b32_dpp v186, v186 row_ror:1 row_mask:0xf bank_mask:0xf bound_ctrl:1
	v_mov_b32_dpp v190, v178 row_ror:2 row_mask:0xf bank_mask:0xf bound_ctrl:1
	v_mov_b32_dpp v187, v187 row_ror:1 row_mask:0xf bank_mask:0xf bound_ctrl:1
	v_mov_b32_dpp v191, v179 row_ror:2 row_mask:0xf bank_mask:0xf bound_ctrl:1
	v_mov_b32_dpp v178, v200 row_ror:1 row_mask:0xf bank_mask:0xf bound_ctrl:1
	v_mov_b32_dpp v180, v180 row_ror:2 row_mask:0xf bank_mask:0xf bound_ctrl:1
	v_mov_b32_dpp v179, v201 row_ror:1 row_mask:0xf bank_mask:0xf bound_ctrl:1
	v_mov_b32_dpp v181, v181 row_ror:2 row_mask:0xf bank_mask:0xf bound_ctrl:1
	s_or_b64 s[0:1], s[0:1], vcc
	s_waitcnt vmcnt(0)
	s_and_saveexec_b64 s[8:9], s[0:1]
	s_xor_b64 s[0:1], exec, s[8:9]
	s_andn2_saveexec_b64 s[0:1], s[0:1]
	s_cbranch_execz .LBB0_122
; __device__ __forceinline__ unsigned pk2(float lo, float hi) { f32x2 v = {lo, hi}; bf16x2_t b = __builtin_convertvector(v, bf16x2_t); return __builtin_bit_cast(unsigned, b); }
; __device__ __forceinline__ float sigmoidf_(float z) { return __builtin_amdgcn_rcpf(1.f + __builtin_amdgcn_exp2f(-z * LOG2E)); }
; __device__ __forceinline__ float dpp_ror1(float v) { return __builtin_bit_cast(float, __builtin_amdgcn_mov_dpp(__builtin_bit_cast(int, v), 0x121, 0xf, 0xf, true)); }
; __device__ __forceinline__ float dpp_ror2(float v) { return __builtin_bit_cast(float, __builtin_amdgcn_mov_dpp(__builtin_bit_cast(int, v), 0x122, 0xf, 0xf, true)); }
;     __device__ __forceinline__ long tok_row(const Unit& u, int ai, int wr, int m, int fr) const {
;         if (u.sp) return (long)((u.pm - 128) * 8 + 4 * ai + 2 * wr + (m >> 1)) * SEQ + (SEQ - 32) + 16 * (m & 1) + fr;
;         const int t = (u.pm & 7) * 254 - 2 + ai * 128 + wr * 64 + m * 16 + fr;
;         return t < 0 ? -1 : (long)(u.pm >> 3) * SEQ + t;
;     __device__ __forceinline__ void operator()(AccT& acc, const Unit& u, int wr, int wc, int fr, int fq, LAS unsigned char* ldsx) const {
;     ...
;                       for (int i = 0; i < 4; ++i) og[i] = wg[n][2][i] * cg[i] + wg[n][1][i] * s1[i] + wg[n][0][i] * s2[i]; }
;                     { float s1[4], s2[4];
; #pragma unroll
;                       for (int i = 0; i < 4; ++i) { s1[i] = hi1 ? pv[n][i] : cv[i]; s2[i] = hi2 ? pv[n][i] : cv[i]; }
; #pragma unroll
;                       for (int i = 0; i < 4; ++i) { s1[i] = dpp_ror1(s1[i]); s2[i] = dpp_ror2(s2[i]); }
; #pragma unroll
;                       for (int i = 0; i < 4; ++i) { const float ov = wv[n][2][i] * cv[i] + wv[n][1][i] * s1[i] + wv[n][0][i] * s2[i]; o[i] = og[i] * sigmoidf_(og[i]) * ov; } }
;                     w[2 * n] = pk2(o[0], o[1]); w[2 * n + 1] = pk2(o[2], o[3]);
;                     pg[n] = cg; pv[n] = cv;
;                 }
;                 const bool st = u.sp ? ((m & 1) != 0) : (ai * 128 + wr * 64 + m * 16 + fr >= 2);
;                 if (st) *(u32x4*)(act + tok_row(u, ai, wr, m, fr) * DFF + ch) = w;
	v_pk_mul_f32 v[200:201], v[158:159], v[126:127]
	v_pk_mul_f32 v[206:207], v[152:153], v[124:125]
	v_pk_fma_f32 v[200:201], v[118:119], v[244:245], v[200:201]
	s_movk_i32 s12, 0x1600
	v_pk_fma_f32 v[200:201], v[114:115], v[240:241], v[200:201]
	v_pk_mul_f32 v[240:241], v[150:151], v[122:123]
	v_mul_f32_e32 v202, 0xbfb8aa3b, v200
	v_exp_f32_e32 v202, v202
	v_mul_f32_e32 v203, 0xbfb8aa3b, v201
	v_exp_f32_e32 v203, v203
	v_pk_fma_f32 v[238:239], v[110:111], v[238:239], v[240:241]
	v_add_f32_e32 v202, 1.0, v202
	v_rcp_f32_e32 v244, v202
	v_add_f32_e32 v202, 1.0, v203
	v_rcp_f32_e32 v245, v202
	v_pk_mul_f32 v[202:203], v[160:161], v[128:129]
	v_pk_fma_f32 v[238:239], v[106:107], v[242:243], v[238:239]
	v_pk_fma_f32 v[202:203], v[120:121], v[232:233], v[202:203]
	v_pk_mul_f32 v[200:201], v[200:201], v[244:245]
	v_pk_fma_f32 v[202:203], v[116:117], v[230:231], v[202:203]
	v_pk_mul_f32 v[200:201], v[200:201], v[238:239]
	v_mul_f32_e32 v219, 0xbfb8aa3b, v202
	v_exp_f32_e32 v219, v219
	v_mul_f32_e32 v221, 0xbfb8aa3b, v203
	v_exp_f32_e32 v221, v221
	v_cvt_pk_bf16_f32 v230, v200, v201
	v_add_f32_e32 v219, 1.0, v219
	v_rcp_f32_e32 v232, v219
	v_add_f32_e32 v219, 1.0, v221
	v_rcp_f32_e32 v233, v219
	v_pk_fma_f32 v[200:201], v[112:113], v[234:235], v[206:207]
	v_pk_mul_f32 v[206:207], v[156:157], v[104:105]
	v_pk_fma_f32 v[200:201], v[108:109], v[236:237], v[200:201]
	v_pk_mul_f32 v[202:203], v[202:203], v[232:233]
	v_pk_fma_f32 v[184:185], v[80:81], v[184:185], v[206:207]
	v_pk_mul_f32 v[200:201], v[202:203], v[200:201]
	v_pk_mul_f32 v[202:203], v[154:155], v[102:103]
	v_pk_fma_f32 v[182:183], v[76:77], v[182:183], v[184:185]
	v_pk_fma_f32 v[192:193], v[78:79], v[192:193], v[202:203]
	v_mul_f32_e32 v184, 0xbfb8aa3b, v182
	v_pk_fma_f32 v[188:189], v[74:75], v[188:189], v[192:193]
	v_cvt_pk_bf16_f32 v231, v200, v201
	v_mul_f32_e32 v192, 0xbfb8aa3b, v188
	v_exp_f32_e32 v202, v192
	v_mul_f32_e32 v192, 0xbfb8aa3b, v189
	v_exp_f32_e32 v203, v192
	v_pk_mul_f32 v[192:193], v[146:147], v[90:91]
	v_add_f32_e32 v202, 1.0, v202
	v_pk_fma_f32 v[186:187], v[70:71], v[186:187], v[192:193]
	v_add_f32_e32 v203, 1.0, v203
	v_rcp_f32_e32 v202, v202
	v_rcp_f32_e32 v203, v203
	v_pk_fma_f32 v[186:187], v[66:67], v[190:191], v[186:187]
	v_exp_f32_e32 v190, v184
	v_mul_f32_e32 v184, 0xbfb8aa3b, v183
	v_exp_f32_e32 v191, v184
	v_pk_mul_f32 v[188:189], v[188:189], v[202:203]
	v_pk_mul_f32 v[200:201], v[148:149], v[92:93]
	v_pk_mul_f32 v[184:185], v[188:189], v[186:187]
	v_add_f32_e32 v186, 1.0, v190
	v_add_f32_e32 v187, 1.0, v191
	v_rcp_f32_e32 v186, v186
	v_rcp_f32_e32 v187, v187
	v_pk_fma_f32 v[178:179], v[72:73], v[178:179], v[200:201]
	v_cmp_lt_i32_e32 vcc, -1, v0
	v_pk_fma_f32 v[178:179], v[68:69], v[180:181], v[178:179]
	v_pk_mul_f32 v[180:181], v[182:183], v[186:187]
	v_cvt_pk_bf16_f32 v232, v184, v185
	v_pk_mul_f32 v[178:179], v[180:181], v[178:179]
	s_nop 0
	v_cvt_pk_bf16_f32 v233, v178, v179
	v_lshl_add_u64 v[178:179], s[64:65], 0, v[0:1]
	v_mad_u64_u32 v[180:181], s[8:9], v178, s12, 0
	v_mad_i32_i24 v179, v179, s12, v181
	v_mov_b32_e32 v178, 0xffffea00
	v_cndmask_b32_e32 v178, v178, v180, vcc
	v_cndmask_b32_e32 v179, -1, v179, vcc
	v_lshl_add_u64 v[178:179], s[52:53], 0, v[178:179]
	v_lshl_add_u64 v[178:179], v[216:217], 1, v[178:179]
	global_store_dwordx4 v[178:179], v[230:233], off

; __device__ __forceinline__ unsigned pk2(float lo, float hi) { f32x2 v = {lo, hi}; bf16x2_t b = __builtin_convertvector(v, bf16x2_t); return __builtin_bit_cast(unsigned, b); }
; __device__ __forceinline__ float sigmoidf_(float z) { return __builtin_amdgcn_rcpf(1.f + __builtin_amdgcn_exp2f(-z * LOG2E)); }
; __device__ __forceinline__ float dpp_ror1(float v) { return __builtin_bit_cast(float, __builtin_amdgcn_mov_dpp(__builtin_bit_cast(int, v), 0x121, 0xf, 0xf, true)); }
; __device__ __forceinline__ float dpp_ror2(float v) { return __builtin_bit_cast(float, __builtin_amdgcn_mov_dpp(__builtin_bit_cast(int, v), 0x122, 0xf, 0xf, true)); }
;     __device__ __forceinline__ void operator()(AccT& acc, const Unit& u, int wr, int wc, int fr, int fq, LAS unsigned char* ldsx) const {
;     ...
;             for (int m = 0; m < 4; ++m) {
;                 u32x4 w;
; #pragma unroll
;                 for (int n = 0; n < 2; ++n) {
;                     const f32x4 cg = acc[ai][0][m][n], cv = acc[ai][1][m][n]; f32x4 o;
;                     float og[4];
;                     { float s1[4], s2[4];
; #pragma unroll
;                       for (int i = 0; i < 4; ++i) { s1[i] = hi1 ? pg[n][i] : cg[i]; s2[i] = hi2 ? pg[n][i] : cg[i]; }
; #pragma unroll
;                       for (int i = 0; i < 4; ++i) { s1[i] = dpp_ror1(s1[i]); s2[i] = dpp_ror2(s2[i]); }
; #pragma unroll
;                       for (int i = 0; i < 4; ++i) og[i] = wg[n][2][i] * cg[i] + wg[n][1][i] * s1[i] + wg[n][0][i] * s2[i]; }
;                     { float s1[4], s2[4];
; #pragma unroll
;                       for (int i = 0; i < 4; ++i) { s1[i] = hi1 ? pv[n][i] : cv[i]; s2[i] = hi2 ? pv[n][i] : cv[i]; }
; #pragma unroll
;                       for (int i = 0; i < 4; ++i) { s1[i] = dpp_ror1(s1[i]); s2[i] = dpp_ror2(s2[i]); }
; #pragma unroll
;                       for (int i = 0; i < 4; ++i) { const float ov = wv[n][2][i] * cv[i] + wv[n][1][i] * s1[i] + wv[n][0][i] * s2[i]; o[i] = og[i] * sigmoidf_(og[i]) * ov; } }
;                     w[2 * n] = pk2(o[0], o[1]); w[2 * n + 1] = pk2(o[2], o[3]);
;                     pg[n] = cg; pv[n] = cv;
;                 }
;                 const bool st = u.sp ? ((m & 1) != 0) : (ai * 128 + wr * 64 + m * 16 + fr >= 2);
;                 if (st) *(u32x4*)(act + tok_row(u, ai, wr, m, fr) * DFF + ch) = w;
.LBB0_127:
	v_pk_mul_f32 v[200:201], v[144:145], v[128:129]
	v_pk_mul_f32 v[206:207], v[136:137], v[124:125]
	v_pk_fma_f32 v[182:183], v[120:121], v[182:183], v[200:201]
	v_pk_fma_f32 v[186:187], v[112:113], v[186:187], v[206:207]
	v_pk_fma_f32 v[180:181], v[116:117], v[180:181], v[182:183]
	v_pk_fma_f32 v[184:185], v[108:109], v[184:185], v[186:187]
	v_mul_f32_e32 v182, 0xbfb8aa3b, v180
	v_mul_f32_e32 v183, 0xbfb8aa3b, v181
	v_exp_f32_e32 v182, v182
	v_exp_f32_e32 v183, v183
	v_pk_mul_f32 v[202:203], v[142:143], v[126:127]
	v_pk_mul_f32 v[186:187], v[130:131], v[90:91]
	v_add_f32_e32 v182, 1.0, v182
	v_add_f32_e32 v183, 1.0, v183
	v_rcp_f32_e32 v182, v182
	v_rcp_f32_e32 v183, v183
	v_pk_fma_f32 v[202:203], v[118:119], v[228:229], v[202:203]
	v_pk_mul_f32 v[228:229], v[134:135], v[122:123]
	v_pk_fma_f32 v[192:193], v[114:115], v[192:193], v[202:203]
	v_pk_mul_f32 v[180:181], v[180:181], v[182:183]
	v_pk_fma_f32 v[190:191], v[110:111], v[190:191], v[228:229]
	v_pk_mul_f32 v[182:183], v[180:181], v[184:185]
	v_pk_mul_f32 v[184:185], v[138:139], v[102:103]
	v_cvt_pk_bf16_f32 v181, v182, v183
	v_pk_mul_f32 v[182:183], v[140:141], v[104:105]
	v_pk_fma_f32 v[178:179], v[78:79], v[178:179], v[184:185]
	v_pk_fma_f32 v[152:153], v[80:81], v[152:153], v[182:183]
	v_pk_fma_f32 v[160:161], v[74:75], v[160:161], v[178:179]
	v_pk_fma_f32 v[150:151], v[76:77], v[150:151], v[152:153]
	v_pk_fma_f32 v[158:159], v[70:71], v[158:159], v[186:187]
	v_mul_f32_e32 v152, 0xbfb8aa3b, v150
	v_mul_f32_e32 v153, 0xbfb8aa3b, v151
	v_exp_f32_e32 v152, v152
	v_exp_f32_e32 v153, v153
	v_mul_f32_e32 v202, 0xbfb8aa3b, v192
	v_pk_fma_f32 v[188:189], v[106:107], v[188:189], v[190:191]
	v_mul_f32_e32 v190, 0xbfb8aa3b, v193
	v_mul_f32_e32 v178, 0xbfb8aa3b, v160
	v_pk_fma_f32 v[156:157], v[66:67], v[156:157], v[158:159]
	v_mul_f32_e32 v158, 0xbfb8aa3b, v161
	v_add_f32_e32 v152, 1.0, v152
	v_add_f32_e32 v153, 1.0, v153
	v_exp_f32_e32 v202, v202
	v_exp_f32_e32 v190, v190
	v_exp_f32_e32 v178, v178
	v_exp_f32_e32 v158, v158
	v_rcp_f32_e32 v152, v152
	v_rcp_f32_e32 v153, v153
	v_pk_mul_f32 v[184:185], v[132:133], v[92:93]
	v_add_f32_e32 v202, 1.0, v202
	v_pk_fma_f32 v[154:155], v[72:73], v[154:155], v[184:185]
	v_add_f32_e32 v190, 1.0, v190
	v_add_f32_e32 v178, 1.0, v178
	v_add_f32_e32 v158, 1.0, v158
	v_pk_fma_f32 v[148:149], v[68:69], v[148:149], v[154:155]
	v_pk_mul_f32 v[150:151], v[150:151], v[152:153]
	v_rcp_f32_e32 v202, v202
	v_rcp_f32_e32 v203, v190
	v_rcp_f32_e32 v178, v178
	v_rcp_f32_e32 v179, v158
	v_pk_mul_f32 v[148:149], v[150:151], v[148:149]
	s_movk_i32 s18, 0x1600
	v_cvt_pk_bf16_f32 v183, v148, v149
	v_mov_b64_e32 v[148:149], s[52:53]
	v_mad_u64_u32 v[148:149], s[8:9], v146, s18, v[148:149]
	v_mov_b32_e32 v146, v149
	v_pk_mul_f32 v[190:191], v[192:193], v[202:203]
	v_pk_mul_f32 v[158:159], v[160:161], v[178:179]
	v_mad_u64_u32 v[146:147], s[8:9], v147, s18, v[146:147]
	v_pk_mul_f32 v[188:189], v[190:191], v[188:189]
	v_pk_mul_f32 v[156:157], v[158:159], v[156:157]
	v_mov_b32_e32 v149, v146
	v_cvt_pk_bf16_f32 v180, v188, v189
	v_cvt_pk_bf16_f32 v182, v156, v157
	v_lshl_add_u64 v[146:147], v[216:217], 1, v[148:149]
	global_store_dwordx4 v[146:147], v[180:183], off
.LBB0_128:
	s_or_b64 exec, exec, s[30:31]
	v_pk_mul_f32 v[88:89], v[88:89], v[226:227] op_sel_hi:[1,0]
	v_pk_mul_f32 v[86:87], v[86:87], v[226:227] op_sel_hi:[1,0]
	v_pk_mul_f32 v[64:65], v[64:65], v[226:227] op_sel_hi:[1,0]
	v_pk_mul_f32 v[62:63], v[62:63], v[226:227] op_sel_hi:[1,0]
	v_pk_mul_f32 v[60:61], v[60:61], v[226:227] op_sel_hi:[1,0]
	v_cndmask_b32_e64 v146, v86, v142, s[42:43]
	v_cndmask_b32_e64 v142, v86, v142, s[40:41]
	v_cndmask_b32_e64 v147, v87, v143, s[42:43]
	v_cndmask_b32_e64 v143, v87, v143, s[40:41]
	v_cndmask_b32_e64 v148, v88, v144, s[42:43]
	v_cndmask_b32_e64 v144, v88, v144, s[40:41]
	v_pk_mul_f32 v[84:85], v[84:85], v[226:227] op_sel_hi:[1,0]
	v_pk_mul_f32 v[82:83], v[82:83], v[226:227] op_sel_hi:[1,0]
	v_cndmask_b32_e64 v149, v89, v145, s[42:43]
	v_cndmask_b32_e64 v145, v89, v145, s[40:41]
	v_mov_b32_dpp v156, v146 row_ror:1 row_mask:0xf bank_mask:0xf bound_ctrl:1
	v_mov_b32_dpp v154, v142 row_ror:2 row_mask:0xf bank_mask:0xf bound_ctrl:1
	v_mov_b32_dpp v155, v143 row_ror:2 row_mask:0xf bank_mask:0xf bound_ctrl:1
	v_mov_b32_dpp v146, v144 row_ror:2 row_mask:0xf bank_mask:0xf bound_ctrl:1
	v_cndmask_b32_e64 v142, v62, v134, s[42:43]
	v_cndmask_b32_e64 v134, v62, v134, s[40:41]
	v_cndmask_b32_e64 v143, v63, v135, s[42:43]
	v_cndmask_b32_e64 v144, v64, v136, s[42:43]
	v_cndmask_b32_e64 v136, v64, v136, s[40:41]
	v_cndmask_b32_e64 v178, v60, v132, s[42:43]
	v_pk_mul_f32 v[58:59], v[58:59], v[226:227] op_sel_hi:[1,0]
	v_mov_b32_dpp v157, v147 row_ror:1 row_mask:0xf bank_mask:0xf bound_ctrl:1
	v_mov_b32_dpp v147, v145 row_ror:2 row_mask:0xf bank_mask:0xf bound_ctrl:1
	v_cndmask_b32_e64 v135, v63, v135, s[40:41]
	v_cndmask_b32_e64 v145, v65, v137, s[42:43]
	v_cndmask_b32_e64 v137, v65, v137, s[40:41]
	v_mov_b32_dpp v160, v142 row_ror:1 row_mask:0xf bank_mask:0xf bound_ctrl:1
	v_mov_b32_dpp v158, v134 row_ror:2 row_mask:0xf bank_mask:0xf bound_ctrl:1
	v_mov_b32_dpp v161, v143 row_ror:1 row_mask:0xf bank_mask:0xf bound_ctrl:1
	v_mov_b32_dpp v150, v136 row_ror:2 row_mask:0xf bank_mask:0xf bound_ctrl:1
	v_cndmask_b32_e64 v134, v82, v138, s[42:43]
	v_cndmask_b32_e64 v136, v83, v139, s[42:43]
	v_cndmask_b32_e64 v142, v84, v140, s[42:43]
	v_cndmask_b32_e64 v143, v84, v140, s[40:41]
	v_cndmask_b32_e64 v179, v60, v132, s[40:41]
	v_mov_b32_dpp v132, v178 row_ror:1 row_mask:0xf bank_mask:0xf bound_ctrl:1
; __device__ __forceinline__ unsigned pk2(float lo, float hi) { f32x2 v = {lo, hi}; bf16x2_t b = __builtin_convertvector(v, bf16x2_t); return __builtin_bit_cast(unsigned, b); }
; __device__ __forceinline__ float sigmoidf_(float z) { return __builtin_amdgcn_rcpf(1.f + __builtin_amdgcn_exp2f(-z * LOG2E)); }
; __device__ __forceinline__ float dpp_ror1(float v) { return __builtin_bit_cast(float, __builtin_amdgcn_mov_dpp(__builtin_bit_cast(int, v), 0x121, 0xf, 0xf, true)); }
; __device__ __forceinline__ float dpp_ror2(float v) { return __builtin_bit_cast(float, __builtin_amdgcn_mov_dpp(__builtin_bit_cast(int, v), 0x122, 0xf, 0xf, true)); }
;     __device__ __forceinline__ void operator()(AccT& acc, const Unit& u, int wr, int wc, int fr, int fq, LAS unsigned char* ldsx) const {
;     ...
;             for (int m = 0; m < 4; ++m) {
;                 u32x4 w;
; #pragma unroll
;                 for (int n = 0; n < 2; ++n) {
;                     const f32x4 cg = acc[ai][0][m][n], cv = acc[ai][1][m][n]; f32x4 o;
;                     float og[4];
;                     { float s1[4], s2[4];
; #pragma unroll
;                       for (int i = 0; i < 4; ++i) { s1[i] = hi1 ? pg[n][i] : cg[i]; s2[i] = hi2 ? pg[n][i] : cg[i]; }
; #pragma unroll
;                       for (int i = 0; i < 4; ++i) { s1[i] = dpp_ror1(s1[i]); s2[i] = dpp_ror2(s2[i]); }
; #pragma unroll
;                       for (int i = 0; i < 4; ++i) og[i] = wg[n][2][i] * cg[i] + wg[n][1][i] * s1[i] + wg[n][0][i] * s2[i]; }
;                     { float s1[4], s2[4];
; #pragma unroll
;                       for (int i = 0; i < 4; ++i) { s1[i] = hi1 ? pv[n][i] : cv[i]; s2[i] = hi2 ? pv[n][i] : cv[i]; }
; #pragma unroll
;                       for (int i = 0; i < 4; ++i) { s1[i] = dpp_ror1(s1[i]); s2[i] = dpp_ror2(s2[i]); }
; #pragma unroll
;                       for (int i = 0; i < 4; ++i) { const float ov = wv[n][2][i] * cv[i] + wv[n][1][i] * s1[i] + wv[n][0][i] * s2[i]; o[i] = og[i] * sigmoidf_(og[i]) * ov; } }
;                     w[2 * n] = pk2(o[0], o[1]); w[2 * n + 1] = pk2(o[2], o[3]);
;                     pg[n] = cg; pv[n] = cv;
;                 }
;                 const bool st = u.sp ? ((m & 1) != 0) : (ai * 128 + wr * 64 + m * 16 + fr >= 2);
;                 if (st) *(u32x4*)(act + tok_row(u, ai, wr, m, fr) * DFF + ch) = w;
	v_add_u32_e32 v178, 32, v204
	v_mov_b32_dpp v159, v135 row_ror:2 row_mask:0xf bank_mask:0xf bound_ctrl:1
	v_mov_b32_dpp v152, v144 row_ror:1 row_mask:0xf bank_mask:0xf bound_ctrl:1
	v_mov_b32_dpp v153, v145 row_ror:1 row_mask:0xf bank_mask:0xf bound_ctrl:1
	v_mov_b32_dpp v151, v137 row_ror:2 row_mask:0xf bank_mask:0xf bound_ctrl:1
	v_cndmask_b32_e64 v135, v82, v138, s[40:41]
	v_cndmask_b32_e64 v137, v83, v139, s[40:41]
	v_cndmask_b32_e64 v144, v85, v141, s[42:43]
	v_cndmask_b32_e64 v145, v85, v141, s[40:41]
	v_mov_b32_dpp v140, v134 row_ror:1 row_mask:0xf bank_mask:0xf bound_ctrl:1
	v_mov_b32_dpp v141, v136 row_ror:1 row_mask:0xf bank_mask:0xf bound_ctrl:1
	v_mov_b32_dpp v136, v142 row_ror:1 row_mask:0xf bank_mask:0xf bound_ctrl:1
	v_mov_b32_dpp v134, v143 row_ror:2 row_mask:0xf bank_mask:0xf bound_ctrl:1
	v_cndmask_b32_e64 v142, v58, v130, s[42:43]
	v_cndmask_b32_e64 v130, v58, v130, s[40:41]
	v_cndmask_b32_e64 v143, v59, v131, s[42:43]
	v_cndmask_b32_e64 v131, v59, v131, s[40:41]
	v_cndmask_b32_e64 v180, v61, v133, s[42:43]
	v_cndmask_b32_e64 v181, v61, v133, s[40:41]
	v_cmp_lt_i32_e32 vcc, 1, v178
	v_mov_b32_dpp v148, v148 row_ror:1 row_mask:0xf bank_mask:0xf bound_ctrl:1
	v_mov_b32_dpp v149, v149 row_ror:1 row_mask:0xf bank_mask:0xf bound_ctrl:1
	v_mov_b32_dpp v138, v135 row_ror:2 row_mask:0xf bank_mask:0xf bound_ctrl:1
	v_mov_b32_dpp v139, v137 row_ror:2 row_mask:0xf bank_mask:0xf bound_ctrl:1
	v_mov_b32_dpp v137, v144 row_ror:1 row_mask:0xf bank_mask:0xf bound_ctrl:1
	v_mov_b32_dpp v135, v145 row_ror:2 row_mask:0xf bank_mask:0xf bound_ctrl:1
	v_mov_b32_dpp v144, v142 row_ror:1 row_mask:0xf bank_mask:0xf bound_ctrl:1
	v_mov_b32_dpp v142, v130 row_ror:2 row_mask:0xf bank_mask:0xf bound_ctrl:1
	v_mov_b32_dpp v145, v143 row_ror:1 row_mask:0xf bank_mask:0xf bound_ctrl:1
	v_mov_b32_dpp v143, v131 row_ror:2 row_mask:0xf bank_mask:0xf bound_ctrl:1
	v_mov_b32_dpp v130, v179 row_ror:2 row_mask:0xf bank_mask:0xf bound_ctrl:1
	v_mov_b32_dpp v133, v180 row_ror:1 row_mask:0xf bank_mask:0xf bound_ctrl:1
	v_mov_b32_dpp v131, v181 row_ror:2 row_mask:0xf bank_mask:0xf bound_ctrl:1
	s_and_b64 s[18:19], s[16:17], vcc
	s_and_saveexec_b64 s[8:9], s[18:19]
	s_cbranch_execz .LBB0_130
	v_pk_mul_f32 v[180:181], v[86:87], v[126:127]
	v_pk_mul_f32 v[182:183], v[88:89], v[128:129]
	v_pk_fma_f32 v[156:157], v[118:119], v[156:157], v[180:181]
	v_pk_fma_f32 v[148:149], v[120:121], v[148:149], v[182:183]
	v_pk_fma_f32 v[154:155], v[114:115], v[154:155], v[156:157]
	v_pk_fma_f32 v[148:149], v[116:117], v[146:147], v[148:149]
	v_mul_f32_e32 v156, 0xbfb8aa3b, v154
	v_exp_f32_e32 v180, v156
	v_mul_f32_e32 v156, 0xbfb8aa3b, v155
	v_exp_f32_e32 v181, v156
	v_pk_mul_f32 v[156:157], v[62:63], v[122:123]
	v_add_f32_e32 v180, 1.0, v180
	v_pk_fma_f32 v[156:157], v[110:111], v[160:161], v[156:157]
	v_add_f32_e32 v181, 1.0, v181
	v_mul_f32_e32 v146, 0xbfb8aa3b, v148
	v_rcp_f32_e32 v180, v180
	v_rcp_f32_e32 v181, v181
	v_pk_fma_f32 v[156:157], v[106:107], v[158:159], v[156:157]
	v_exp_f32_e32 v158, v146
	v_mul_f32_e32 v146, 0xbfb8aa3b, v149
	v_exp_f32_e32 v159, v146
	v_pk_mul_f32 v[154:155], v[154:155], v[180:181]
	v_pk_mul_f32 v[178:179], v[64:65], v[124:125]
	v_pk_mul_f32 v[146:147], v[154:155], v[156:157]
	v_add_f32_e32 v154, 1.0, v158
	v_add_f32_e32 v155, 1.0, v159
	v_rcp_f32_e32 v154, v154
	v_rcp_f32_e32 v155, v155
	v_pk_fma_f32 v[152:153], v[112:113], v[152:153], v[178:179]
	v_cvt_pk_bf16_f32 v146, v146, v147
	v_pk_fma_f32 v[150:151], v[108:109], v[150:151], v[152:153]
	v_pk_mul_f32 v[148:149], v[148:149], v[154:155]
	v_pk_mul_f32 v[152:153], v[84:85], v[104:105]
	v_pk_mul_f32 v[148:149], v[148:149], v[150:151]
	v_pk_fma_f32 v[136:137], v[80:81], v[136:137], v[152:153]
	v_cvt_pk_bf16_f32 v147, v148, v149
	v_pk_mul_f32 v[148:149], v[82:83], v[102:103]
	v_pk_fma_f32 v[134:135], v[76:77], v[134:135], v[136:137]
	v_pk_fma_f32 v[140:141], v[78:79], v[140:141], v[148:149]
	v_mul_f32_e32 v136, 0xbfb8aa3b, v134
	v_pk_fma_f32 v[138:139], v[74:75], v[138:139], v[140:141]
	v_pk_mul_f32 v[150:151], v[60:61], v[92:93]
	v_mul_f32_e32 v140, 0xbfb8aa3b, v138
	v_exp_f32_e32 v148, v140
	v_mul_f32_e32 v140, 0xbfb8aa3b, v139
	v_exp_f32_e32 v149, v140
	v_pk_mul_f32 v[140:141], v[58:59], v[90:91]
	v_add_f32_e32 v148, 1.0, v148
	v_pk_fma_f32 v[140:141], v[70:71], v[144:145], v[140:141]
	v_add_f32_e32 v149, 1.0, v149
	v_rcp_f32_e32 v148, v148
	v_rcp_f32_e32 v149, v149
	v_pk_fma_f32 v[140:141], v[66:67], v[142:143], v[140:141]
	v_exp_f32_e32 v142, v136
	v_mul_f32_e32 v136, 0xbfb8aa3b, v135
	v_exp_f32_e32 v143, v136
	v_pk_mul_f32 v[138:139], v[138:139], v[148:149]
	v_pk_fma_f32 v[132:133], v[72:73], v[132:133], v[150:151]
	v_pk_mul_f32 v[136:137], v[138:139], v[140:141]
	v_add_f32_e32 v138, 1.0, v142
	v_add_f32_e32 v139, 1.0, v143
	v_rcp_f32_e32 v138, v138
	v_rcp_f32_e32 v139, v139
	v_pk_fma_f32 v[130:131], v[68:69], v[130:131], v[132:133]
	v_mov_b32_e32 v221, v1
	s_movk_i32 s22, 0x1600
	v_pk_mul_f32 v[132:133], v[134:135], v[138:139]
	v_cmp_lt_i32_e32 vcc, -1, v220
	v_pk_mul_f32 v[130:131], v[132:133], v[130:131]
	v_cvt_pk_bf16_f32 v148, v136, v137
	v_cvt_pk_bf16_f32 v149, v130, v131
	v_lshl_add_u64 v[130:131], s[64:65], 0, v[220:221]
	v_mad_u64_u32 v[132:133], s[18:19], v130, s22, 0
	v_mad_i32_i24 v131, v131, s22, v133
	v_mov_b32_e32 v130, 0xffffea00
	v_cndmask_b32_e32 v130, v130, v132, vcc
	v_cndmask_b32_e32 v131, -1, v131, vcc
	v_lshl_add_u64 v[130:131], s[52:53], 0, v[130:131]
	v_lshl_add_u64 v[130:131], v[216:217], 1, v[130:131]
	global_store_dwordx4 v[130:131], v[146:149], off

; __device__ __forceinline__ unsigned pk2(float lo, float hi) { f32x2 v = {lo, hi}; bf16x2_t b = __builtin_convertvector(v, bf16x2_t); return __builtin_bit_cast(unsigned, b); }
; __device__ __forceinline__ float sigmoidf_(float z) { return __builtin_amdgcn_rcpf(1.f + __builtin_amdgcn_exp2f(-z * LOG2E)); }
; __device__ __forceinline__ float dpp_ror1(float v) { return __builtin_bit_cast(float, __builtin_amdgcn_mov_dpp(__builtin_bit_cast(int, v), 0x121, 0xf, 0xf, true)); }
; __device__ __forceinline__ float dpp_ror2(float v) { return __builtin_bit_cast(float, __builtin_amdgcn_mov_dpp(__builtin_bit_cast(int, v), 0x122, 0xf, 0xf, true)); }
;     __device__ __forceinline__ void operator()(AccT& acc, const Unit& u, int wr, int wc, int fr, int fq, LAS unsigned char* ldsx) const {
;     ...
;             for (int m = 0; m < 4; ++m) {
;                 u32x4 w;
; #pragma unroll
;                 for (int n = 0; n < 2; ++n) {
;                     const f32x4 cg = acc[ai][0][m][n], cv = acc[ai][1][m][n]; f32x4 o;
;                     float og[4];
;                     { float s1[4], s2[4];
; #pragma unroll
;                       for (int i = 0; i < 4; ++i) { s1[i] = hi1 ? pg[n][i] : cg[i]; s2[i] = hi2 ? pg[n][i] : cg[i]; }
; #pragma unroll
;                       for (int i = 0; i < 4; ++i) { s1[i] = dpp_ror1(s1[i]); s2[i] = dpp_ror2(s2[i]); }
; #pragma unroll
;                       for (int i = 0; i < 4; ++i) og[i] = wg[n][2][i] * cg[i] + wg[n][1][i] * s1[i] + wg[n][0][i] * s2[i]; }
;                     { float s1[4], s2[4];
; #pragma unroll
;                       for (int i = 0; i < 4; ++i) { s1[i] = hi1 ? pv[n][i] : cv[i]; s2[i] = hi2 ? pv[n][i] : cv[i]; }
; #pragma unroll
;                       for (int i = 0; i < 4; ++i) { s1[i] = dpp_ror1(s1[i]); s2[i] = dpp_ror2(s2[i]); }
; #pragma unroll
;                       for (int i = 0; i < 4; ++i) { const float ov = wv[n][2][i] * cv[i] + wv[n][1][i] * s1[i] + wv[n][0][i] * s2[i]; o[i] = og[i] * sigmoidf_(og[i]) * ov; } }
;                     w[2 * n] = pk2(o[0], o[1]); w[2 * n + 1] = pk2(o[2], o[3]);
;                     pg[n] = cg; pv[n] = cv;
;                 }
;                 const bool st = u.sp ? ((m & 1) != 0) : (ai * 128 + wr * 64 + m * 16 + fr >= 2);
;                 if (st) *(u32x4*)(act + tok_row(u, ai, wr, m, fr) * DFF + ch) = w;
.LBB0_135:
	v_pk_mul_f32 v[148:149], v[170:171], v[126:127]
	v_pk_mul_f32 v[152:153], v[174:175], v[122:123]
	v_pk_fma_f32 v[146:147], v[118:119], v[146:147], v[148:149]
	v_pk_fma_f32 v[142:143], v[110:111], v[142:143], v[152:153]
	v_pk_fma_f32 v[144:145], v[114:115], v[144:145], v[146:147]
	v_pk_fma_f32 v[140:141], v[106:107], v[140:141], v[142:143]
	v_mul_f32_e32 v151, 0xbfb8aa3b, v145
	v_mul_f32_e32 v146, 0xbfb8aa3b, v144
	v_exp_f32_e32 v151, v151
	v_exp_f32_e32 v150, v146
	v_pk_mul_f32 v[146:147], v[172:173], v[128:129]
	v_pk_mul_f32 v[148:149], v[176:177], v[124:125]
	v_pk_fma_f32 v[138:139], v[120:121], v[138:139], v[146:147]
	v_add_f32_e32 v142, 1.0, v151
	v_pk_fma_f32 v[136:137], v[116:117], v[136:137], v[138:139]
	v_rcp_f32_e32 v151, v142
	v_mul_f32_e32 v138, 0xbfb8aa3b, v136
	v_exp_f32_e32 v142, v138
	v_mul_f32_e32 v138, 0xbfb8aa3b, v137
	v_exp_f32_e32 v143, v138
	v_pk_fma_f32 v[134:135], v[112:113], v[134:135], v[148:149]
	v_add_f32_e32 v142, 1.0, v142
	v_rcp_f32_e32 v142, v142
	v_add_f32_e32 v143, 1.0, v143
	v_rcp_f32_e32 v143, v143
	v_add_f32_e32 v150, 1.0, v150
	v_pk_fma_f32 v[132:133], v[108:109], v[132:133], v[134:135]
	v_rcp_f32_e32 v150, v150
	v_pk_mul_f32 v[134:135], v[136:137], v[142:143]
	v_pk_mul_f32 v[136:137], v[168:169], v[92:93]
	v_pk_mul_f32 v[132:133], v[134:135], v[132:133]
	v_pk_mul_f32 v[134:135], v[162:163], v[102:103]
	v_pk_mul_f32 v[138:139], v[144:145], v[150:151]
	v_pk_fma_f32 v[130:131], v[78:79], v[130:131], v[134:135]
	v_pk_mul_f32 v[138:139], v[138:139], v[140:141]
	v_pk_fma_f32 v[88:89], v[74:75], v[88:89], v[130:131]
	v_cvt_pk_bf16_f32 v131, v132, v133
	v_mul_f32_e32 v135, 0xbfb8aa3b, v89
	v_exp_f32_e32 v135, v135
	v_mul_f32_e32 v130, 0xbfb8aa3b, v88
	v_pk_mul_f32 v[132:133], v[164:165], v[104:105]
	v_exp_f32_e32 v134, v130
	v_cvt_pk_bf16_f32 v130, v138, v139
	v_pk_mul_f32 v[138:139], v[166:167], v[90:91]
	v_pk_fma_f32 v[64:65], v[80:81], v[64:65], v[132:133]
	v_pk_fma_f32 v[86:87], v[70:71], v[86:87], v[138:139]
	v_pk_fma_f32 v[62:63], v[76:77], v[62:63], v[64:65]
	v_pk_fma_f32 v[84:85], v[66:67], v[84:85], v[86:87]
	v_add_f32_e32 v86, 1.0, v135
	v_mul_f32_e32 v64, 0xbfb8aa3b, v62
	v_rcp_f32_e32 v135, v86
	v_exp_f32_e32 v86, v64
	v_mul_f32_e32 v64, 0xbfb8aa3b, v63
	v_exp_f32_e32 v87, v64
	v_pk_fma_f32 v[60:61], v[72:73], v[60:61], v[136:137]
	v_add_f32_e32 v86, 1.0, v86
	v_rcp_f32_e32 v86, v86
	v_add_f32_e32 v87, 1.0, v87
	v_rcp_f32_e32 v87, v87
	v_add_f32_e32 v134, 1.0, v134
	v_pk_fma_f32 v[58:59], v[68:69], v[58:59], v[60:61]
	v_rcp_f32_e32 v134, v134
	v_pk_mul_f32 v[60:61], v[62:63], v[86:87]
	s_movk_i32 s18, 0x1600
	v_pk_mul_f32 v[58:59], v[60:61], v[58:59]
	v_pk_mul_f32 v[64:65], v[88:89], v[134:135]
	v_cvt_pk_bf16_f32 v133, v58, v59
	v_mov_b64_e32 v[58:59], s[52:53]
	v_mad_u64_u32 v[58:59], s[8:9], v82, s18, v[58:59]
	v_mov_b32_e32 v60, v59
	v_mad_u64_u32 v[60:61], s[8:9], v83, s18, v[60:61]
	v_pk_mul_f32 v[64:65], v[64:65], v[84:85]
	v_mov_b32_e32 v59, v60
	v_cvt_pk_bf16_f32 v132, v64, v65
	v_lshl_add_u64 v[58:59], v[216:217], 1, v[58:59]
	global_store_dwordx4 v[58:59], v[130:133], off

; #define LAS __attribute__((address_space(3)))
; __device__ __forceinline__ float dpp_ror1(float v) { return __builtin_bit_cast(float, __builtin_amdgcn_mov_dpp(__builtin_bit_cast(int, v), 0x121, 0xf, 0xf, true)); }
; __device__ __forceinline__ float dpp_ror2(float v) { return __builtin_bit_cast(float, __builtin_amdgcn_mov_dpp(__builtin_bit_cast(int, v), 0x122, 0xf, 0xf, true)); }
;     __device__ __forceinline__ void operator()(AccT& acc, const Unit& u, int wr, int wc, int fr, int fq, LAS unsigned char* ldsx) const {
;     ...
;         for (int ai = 0; ai < 2; ++ai) {
;             const int s = ai * 2 + wr;
;             f32x4 pg[2], pv[2];
; #pragma unroll
;             for (int n = 0; n < 2; ++n) { pg[n] = (f32x4){0.f, 0.f, 0.f, 0.f}; pv[n] = pg[n]; }
;             if (s > 0 && fr >= 14) {
; #pragma unroll
;                 for (int n = 0; n < 2; ++n) { const LAS float* q = xch + (((s - 1) * 2 + (fr - 14)) * 256 + wc * 32 + n * 16 + 4 * fq); pg[n] = *(const LAS f32x4*)q; pv[n] = *(const LAS f32x4*)(q + 128); }
;             }
; #pragma unroll
;             for (int m = 0; m < 4; ++m) {
;                 u32x4 w;
; #pragma unroll
;                 for (int n = 0; n < 2; ++n) {
;                     const f32x4 cg = acc[ai][0][m][n], cv = acc[ai][1][m][n]; f32x4 o;
;                     float og[4];
;                     { float s1[4], s2[4];
; #pragma unroll
;                       for (int i = 0; i < 4; ++i) { s1[i] = hi1 ? pg[n][i] : cg[i]; s2[i] = hi2 ? pg[n][i] : cg[i]; }
; #pragma unroll
;                       for (int i = 0; i < 4; ++i) { s1[i] = dpp_ror1(s1[i]); s2[i] = dpp_ror2(s2[i]); }
; #pragma unroll
;                       for (int i = 0; i < 4; ++i) og[i] = wg[n][2][i] * cg[i] + wg[n][1][i] * s1[i] + wg[n][0][i] * s2[i]; }
.LBB0_138:
	s_or_b64 exec, exec, s[8:9]
	v_pk_mul_f32 v[130:131], v[46:47], v[224:225] op_sel_hi:[1,0]
	v_pk_mul_f32 v[46:47], v[40:41], v[224:225] op_sel_hi:[1,0]
	v_pk_mul_f32 v[38:39], v[38:39], v[224:225] op_sel_hi:[1,0]
	v_pk_mul_f32 v[40:41], v[36:37], v[224:225] op_sel_hi:[1,0]
	s_waitcnt lgkmcnt(3)
	v_cndmask_b32_e64 v36, v130, v86, s[42:43]
	v_cndmask_b32_e64 v37, v130, v86, s[40:41]
	v_cndmask_b32_e64 v86, v131, v87, s[42:43]
	v_cndmask_b32_e64 v87, v131, v87, s[40:41]
	v_pk_mul_f32 v[44:45], v[44:45], v[224:225] op_sel_hi:[1,0]
	v_pk_mul_f32 v[42:43], v[42:43], v[224:225] op_sel_hi:[1,0]
	v_mov_b32_dpp v140, v36 row_ror:1 row_mask:0xf bank_mask:0xf bound_ctrl:1
	v_mov_b32_dpp v138, v37 row_ror:2 row_mask:0xf bank_mask:0xf bound_ctrl:1
	v_mov_b32_dpp v141, v86 row_ror:1 row_mask:0xf bank_mask:0xf bound_ctrl:1
	v_mov_b32_dpp v139, v87 row_ror:2 row_mask:0xf bank_mask:0xf bound_ctrl:1
	s_waitcnt lgkmcnt(1)
	v_cndmask_b32_e64 v36, v38, v82, s[42:43]
	v_cndmask_b32_e64 v37, v38, v82, s[40:41]
	v_cndmask_b32_e64 v86, v46, v84, s[42:43]
	v_cndmask_b32_e64 v84, v46, v84, s[40:41]
	v_cndmask_b32_e64 v87, v47, v85, s[42:43]
	v_cndmask_b32_e64 v85, v47, v85, s[40:41]
	s_waitcnt lgkmcnt(0)
	v_cndmask_b32_e64 v146, v40, v60, s[42:43]
	v_pk_mul_f32 v[48:49], v[48:49], v[224:225] op_sel_hi:[1,0]
	v_pk_mul_f32 v[34:35], v[34:35], v[224:225] op_sel_hi:[1,0]
	v_cndmask_b32_e64 v82, v39, v83, s[42:43]
	v_cndmask_b32_e64 v83, v39, v83, s[40:41]
	v_mov_b32_dpp v144, v36 row_ror:1 row_mask:0xf bank_mask:0xf bound_ctrl:1
	v_mov_b32_dpp v142, v37 row_ror:2 row_mask:0xf bank_mask:0xf bound_ctrl:1
	v_mov_b32_dpp v134, v84 row_ror:2 row_mask:0xf bank_mask:0xf bound_ctrl:1
	v_mov_b32_dpp v135, v85 row_ror:2 row_mask:0xf bank_mask:0xf bound_ctrl:1
	v_cndmask_b32_e64 v36, v42, v62, s[42:43]
	v_cndmask_b32_e64 v37, v42, v62, s[40:41]
	v_cndmask_b32_e64 v62, v43, v63, s[42:43]
	v_cndmask_b32_e64 v84, v44, v64, s[42:43]
	v_cndmask_b32_e64 v85, v44, v64, s[40:41]
	v_cndmask_b32_e64 v147, v40, v60, s[40:41]
	v_mov_b32_dpp v60, v146 row_ror:1 row_mask:0xf bank_mask:0xf bound_ctrl:1
	v_add_u32_e32 v146, 0x80, v204
	v_cndmask_b32_e64 v132, v48, v88, s[42:43]
	v_cndmask_b32_e64 v88, v48, v88, s[40:41]
	v_cndmask_b32_e64 v133, v49, v89, s[42:43]
	v_cndmask_b32_e64 v89, v49, v89, s[40:41]
	v_mov_b32_dpp v145, v82 row_ror:1 row_mask:0xf bank_mask:0xf bound_ctrl:1
	v_mov_b32_dpp v143, v83 row_ror:2 row_mask:0xf bank_mask:0xf bound_ctrl:1
	v_mov_b32_dpp v136, v86 row_ror:1 row_mask:0xf bank_mask:0xf bound_ctrl:1
	v_mov_b32_dpp v137, v87 row_ror:1 row_mask:0xf bank_mask:0xf bound_ctrl:1
	v_cndmask_b32_e64 v63, v43, v63, s[40:41]
	v_cndmask_b32_e64 v86, v45, v65, s[42:43]
	v_cndmask_b32_e64 v87, v45, v65, s[40:41]
	v_mov_b32_dpp v82, v36 row_ror:1 row_mask:0xf bank_mask:0xf bound_ctrl:1
	v_mov_b32_dpp v83, v62 row_ror:1 row_mask:0xf bank_mask:0xf bound_ctrl:1
	v_mov_b32_dpp v62, v84 row_ror:1 row_mask:0xf bank_mask:0xf bound_ctrl:1
	v_mov_b32_dpp v36, v85 row_ror:2 row_mask:0xf bank_mask:0xf bound_ctrl:1
	v_cndmask_b32_e64 v84, v34, v58, s[42:43]
	v_cndmask_b32_e64 v58, v34, v58, s[40:41]
	v_cndmask_b32_e64 v85, v35, v59, s[42:43]
	v_cndmask_b32_e64 v59, v35, v59, s[40:41]
	v_cndmask_b32_e64 v148, v41, v61, s[42:43]
	v_cndmask_b32_e64 v149, v41, v61, s[40:41]
	v_cmp_lt_i32_e32 vcc, 1, v146
	v_mov_b32_dpp v132, v132 row_ror:1 row_mask:0xf bank_mask:0xf bound_ctrl:1
	v_mov_b32_dpp v88, v88 row_ror:2 row_mask:0xf bank_mask:0xf bound_ctrl:1
	v_mov_b32_dpp v133, v133 row_ror:1 row_mask:0xf bank_mask:0xf bound_ctrl:1
	v_mov_b32_dpp v89, v89 row_ror:2 row_mask:0xf bank_mask:0xf bound_ctrl:1
	v_mov_b32_dpp v64, v37 row_ror:2 row_mask:0xf bank_mask:0xf bound_ctrl:1
	v_mov_b32_dpp v65, v63 row_ror:2 row_mask:0xf bank_mask:0xf bound_ctrl:1
	v_mov_b32_dpp v63, v86 row_ror:1 row_mask:0xf bank_mask:0xf bound_ctrl:1
	v_mov_b32_dpp v37, v87 row_ror:2 row_mask:0xf bank_mask:0xf bound_ctrl:1
	v_mov_b32_dpp v86, v84 row_ror:1 row_mask:0xf bank_mask:0xf bound_ctrl:1
	v_mov_b32_dpp v84, v58 row_ror:2 row_mask:0xf bank_mask:0xf bound_ctrl:1
	v_mov_b32_dpp v87, v85 row_ror:1 row_mask:0xf bank_mask:0xf bound_ctrl:1
	v_mov_b32_dpp v85, v59 row_ror:2 row_mask:0xf bank_mask:0xf bound_ctrl:1
	v_mov_b32_dpp v58, v147 row_ror:2 row_mask:0xf bank_mask:0xf bound_ctrl:1
	v_mov_b32_dpp v61, v148 row_ror:1 row_mask:0xf bank_mask:0xf bound_ctrl:1
	v_mov_b32_dpp v59, v149 row_ror:2 row_mask:0xf bank_mask:0xf bound_ctrl:1
	s_and_b64 s[18:19], s[16:17], vcc
	s_and_saveexec_b64 s[8:9], s[18:19]
	s_cbranch_execz .LBB0_140
; __device__ __forceinline__ unsigned pk2(float lo, float hi) { f32x2 v = {lo, hi}; bf16x2_t b = __builtin_convertvector(v, bf16x2_t); return __builtin_bit_cast(unsigned, b); }
; __device__ __forceinline__ float sigmoidf_(float z) { return __builtin_amdgcn_rcpf(1.f + __builtin_amdgcn_exp2f(-z * LOG2E)); }
; __device__ __forceinline__ float dpp_ror1(float v) { return __builtin_bit_cast(float, __builtin_amdgcn_mov_dpp(__builtin_bit_cast(int, v), 0x121, 0xf, 0xf, true)); }
; __device__ __forceinline__ float dpp_ror2(float v) { return __builtin_bit_cast(float, __builtin_amdgcn_mov_dpp(__builtin_bit_cast(int, v), 0x122, 0xf, 0xf, true)); }
;     __device__ __forceinline__ void operator()(AccT& acc, const Unit& u, int wr, int wc, int fr, int fq, LAS unsigned char* ldsx) const {
;     ...
;                       for (int i = 0; i < 4; ++i) og[i] = wg[n][2][i] * cg[i] + wg[n][1][i] * s1[i] + wg[n][0][i] * s2[i]; }
;                     { float s1[4], s2[4];
; #pragma unroll
;                       for (int i = 0; i < 4; ++i) { s1[i] = hi1 ? pv[n][i] : cv[i]; s2[i] = hi2 ? pv[n][i] : cv[i]; }
; #pragma unroll
;                       for (int i = 0; i < 4; ++i) { s1[i] = dpp_ror1(s1[i]); s2[i] = dpp_ror2(s2[i]); }
; #pragma unroll
;                       for (int i = 0; i < 4; ++i) { const float ov = wv[n][2][i] * cv[i] + wv[n][1][i] * s1[i] + wv[n][0][i] * s2[i]; o[i] = og[i] * sigmoidf_(og[i]) * ov; } }
;                     w[2 * n] = pk2(o[0], o[1]); w[2 * n + 1] = pk2(o[2], o[3]);
;                     pg[n] = cg; pv[n] = cv;
;                 }
;                 const bool st = u.sp ? ((m & 1) != 0) : (ai * 128 + wr * 64 + m * 16 + fr >= 2);
;                 if (st) *(u32x4*)(act + tok_row(u, ai, wr, m, fr) * DFF + ch) = w;
	v_pk_mul_f32 v[148:149], v[130:131], v[126:127]
	v_pk_mul_f32 v[150:151], v[48:49], v[128:129]
	v_pk_fma_f32 v[140:141], v[118:119], v[140:141], v[148:149]
	v_pk_fma_f32 v[132:133], v[120:121], v[132:133], v[150:151]
	v_pk_fma_f32 v[138:139], v[114:115], v[138:139], v[140:141]
	v_pk_fma_f32 v[88:89], v[116:117], v[88:89], v[132:133]
	v_mul_f32_e32 v140, 0xbfb8aa3b, v138
	v_exp_f32_e32 v148, v140
	v_mul_f32_e32 v140, 0xbfb8aa3b, v139
	v_exp_f32_e32 v149, v140
	v_pk_mul_f32 v[140:141], v[38:39], v[122:123]
	v_add_f32_e32 v148, 1.0, v148
	v_pk_fma_f32 v[140:141], v[110:111], v[144:145], v[140:141]
	v_add_f32_e32 v149, 1.0, v149
	v_mul_f32_e32 v132, 0xbfb8aa3b, v88
	v_rcp_f32_e32 v148, v148
	v_rcp_f32_e32 v149, v149
	v_pk_fma_f32 v[140:141], v[106:107], v[142:143], v[140:141]
	v_exp_f32_e32 v142, v132
	v_mul_f32_e32 v132, 0xbfb8aa3b, v89
	v_exp_f32_e32 v143, v132
	v_pk_mul_f32 v[138:139], v[138:139], v[148:149]
	v_pk_mul_f32 v[146:147], v[46:47], v[124:125]
	v_pk_mul_f32 v[132:133], v[138:139], v[140:141]
	v_add_f32_e32 v138, 1.0, v142
	v_add_f32_e32 v139, 1.0, v143
	v_rcp_f32_e32 v138, v138
	v_rcp_f32_e32 v139, v139
	v_pk_fma_f32 v[136:137], v[112:113], v[136:137], v[146:147]
	v_cvt_pk_bf16_f32 v132, v132, v133
	v_pk_fma_f32 v[134:135], v[108:109], v[134:135], v[136:137]
	v_pk_mul_f32 v[88:89], v[88:89], v[138:139]
	v_pk_mul_f32 v[136:137], v[44:45], v[104:105]
	v_pk_mul_f32 v[88:89], v[88:89], v[134:135]
	v_pk_mul_f32 v[134:135], v[42:43], v[102:103]
	v_pk_fma_f32 v[62:63], v[80:81], v[62:63], v[136:137]
	v_pk_fma_f32 v[82:83], v[78:79], v[82:83], v[134:135]
	v_pk_fma_f32 v[36:37], v[76:77], v[36:37], v[62:63]
	v_pk_fma_f32 v[64:65], v[74:75], v[64:65], v[82:83]
	v_mul_f32_e32 v62, 0xbfb8aa3b, v36
	v_mul_f32_e32 v82, 0xbfb8aa3b, v64
	v_exp_f32_e32 v134, v82
	v_mul_f32_e32 v82, 0xbfb8aa3b, v65
	v_exp_f32_e32 v135, v82
	v_pk_mul_f32 v[82:83], v[34:35], v[90:91]
	v_add_f32_e32 v134, 1.0, v134
	v_pk_fma_f32 v[82:83], v[70:71], v[86:87], v[82:83]
	v_add_f32_e32 v135, 1.0, v135
	v_rcp_f32_e32 v134, v134
	v_rcp_f32_e32 v135, v135
	v_pk_fma_f32 v[82:83], v[66:67], v[84:85], v[82:83]
	v_exp_f32_e32 v84, v62
	v_mul_f32_e32 v62, 0xbfb8aa3b, v37
	v_exp_f32_e32 v85, v62
	v_pk_mul_f32 v[64:65], v[64:65], v[134:135]
	v_cvt_pk_bf16_f32 v133, v88, v89
	v_pk_mul_f32 v[62:63], v[64:65], v[82:83]
	v_add_f32_e32 v64, 1.0, v84
	v_add_f32_e32 v65, 1.0, v85
	v_rcp_f32_e32 v64, v64
	v_rcp_f32_e32 v65, v65
	v_pk_mul_f32 v[88:89], v[40:41], v[92:93]
	v_mov_b32_e32 v219, v1
	v_pk_fma_f32 v[60:61], v[72:73], v[60:61], v[88:89]
	v_pk_mul_f32 v[36:37], v[36:37], v[64:65]
	v_pk_fma_f32 v[58:59], v[68:69], v[58:59], v[60:61]
	s_movk_i32 s22, 0x1600
	v_pk_mul_f32 v[36:37], v[36:37], v[58:59]
	v_cmp_lt_i32_e32 vcc, -1, v218
	v_cvt_pk_bf16_f32 v135, v36, v37
	v_lshl_add_u64 v[36:37], s[64:65], 0, v[218:219]
	v_mad_u64_u32 v[58:59], s[18:19], v36, s22, 0
	v_mad_i32_i24 v37, v37, s22, v59
	v_mov_b32_e32 v36, 0xffffea00
	v_cndmask_b32_e32 v36, v36, v58, vcc
	v_cndmask_b32_e32 v37, -1, v37, vcc
	v_lshl_add_u64 v[36:37], s[52:53], 0, v[36:37]
	v_cvt_pk_bf16_f32 v134, v62, v63
	v_lshl_add_u64 v[36:37], v[216:217], 1, v[36:37]
	global_store_dwordx4 v[36:37], v[132:135], off

; __device__ __forceinline__ unsigned pk2(float lo, float hi) { f32x2 v = {lo, hi}; bf16x2_t b = __builtin_convertvector(v, bf16x2_t); return __builtin_bit_cast(unsigned, b); }
; __device__ __forceinline__ float sigmoidf_(float z) { return __builtin_amdgcn_rcpf(1.f + __builtin_amdgcn_exp2f(-z * LOG2E)); }
; __device__ __forceinline__ float dpp_ror1(float v) { return __builtin_bit_cast(float, __builtin_amdgcn_mov_dpp(__builtin_bit_cast(int, v), 0x121, 0xf, 0xf, true)); }
; __device__ __forceinline__ float dpp_ror2(float v) { return __builtin_bit_cast(float, __builtin_amdgcn_mov_dpp(__builtin_bit_cast(int, v), 0x122, 0xf, 0xf, true)); }
;     __device__ __forceinline__ void operator()(AccT& acc, const Unit& u, int wr, int wc, int fr, int fq, LAS unsigned char* ldsx) const {
;     ...
;             for (int m = 0; m < 4; ++m) {
;                 u32x4 w;
; #pragma unroll
;                 for (int n = 0; n < 2; ++n) {
;                     const f32x4 cg = acc[ai][0][m][n], cv = acc[ai][1][m][n]; f32x4 o;
;                     float og[4];
;                     { float s1[4], s2[4];
; #pragma unroll
;                       for (int i = 0; i < 4; ++i) { s1[i] = hi1 ? pg[n][i] : cg[i]; s2[i] = hi2 ? pg[n][i] : cg[i]; }
; #pragma unroll
;                       for (int i = 0; i < 4; ++i) { s1[i] = dpp_ror1(s1[i]); s2[i] = dpp_ror2(s2[i]); }
; #pragma unroll
;                       for (int i = 0; i < 4; ++i) og[i] = wg[n][2][i] * cg[i] + wg[n][1][i] * s1[i] + wg[n][0][i] * s2[i]; }
;                     { float s1[4], s2[4];
; #pragma unroll
;                       for (int i = 0; i < 4; ++i) { s1[i] = hi1 ? pv[n][i] : cv[i]; s2[i] = hi2 ? pv[n][i] : cv[i]; }
; #pragma unroll
;                       for (int i = 0; i < 4; ++i) { s1[i] = dpp_ror1(s1[i]); s2[i] = dpp_ror2(s2[i]); }
; #pragma unroll
;                       for (int i = 0; i < 4; ++i) { const float ov = wv[n][2][i] * cv[i] + wv[n][1][i] * s1[i] + wv[n][0][i] * s2[i]; o[i] = og[i] * sigmoidf_(og[i]) * ov; } }
;                     w[2 * n] = pk2(o[0], o[1]); w[2 * n + 1] = pk2(o[2], o[3]);
;                     pg[n] = cg; pv[n] = cv;
;                 }
;                 const bool st = u.sp ? ((m & 1) != 0) : (ai * 128 + wr * 64 + m * 16 + fr >= 2);
;                 if (st) *(u32x4*)(act + tok_row(u, ai, wr, m, fr) * DFF + ch) = w;
.LBB0_145:
	v_pk_mul_f32 v[132:133], v[32:33], v[128:129]
	v_pk_mul_f32 v[134:135], v[30:31], v[126:127]
	v_pk_fma_f32 v[62:63], v[120:121], v[62:63], v[132:133]
	v_pk_fma_f32 v[130:131], v[118:119], v[130:131], v[134:135]
	v_pk_fma_f32 v[60:61], v[116:117], v[60:61], v[62:63]
	v_pk_mul_f32 v[134:135], v[24:25], v[124:125]
	v_mul_f32_e32 v62, 0xbfb8aa3b, v60
	v_mul_f32_e32 v63, 0xbfb8aa3b, v61
	v_exp_f32_e32 v62, v62
	v_exp_f32_e32 v63, v63
	v_pk_fma_f32 v[82:83], v[112:113], v[82:83], v[134:135]
	v_pk_mul_f32 v[136:137], v[22:23], v[122:123]
	v_add_f32_e32 v62, 1.0, v62
	v_add_f32_e32 v63, 1.0, v63
	v_rcp_f32_e32 v62, v62
	v_rcp_f32_e32 v63, v63
	v_pk_fma_f32 v[64:65], v[108:109], v[64:65], v[82:83]
	v_pk_mul_f32 v[82:83], v[18:19], v[90:91]
	v_pk_fma_f32 v[88:89], v[114:115], v[88:89], v[130:131]
	v_pk_mul_f32 v[60:61], v[60:61], v[62:63]
	v_pk_fma_f32 v[86:87], v[110:111], v[86:87], v[136:137]
	v_pk_mul_f32 v[62:63], v[60:61], v[64:65]
	v_pk_mul_f32 v[64:65], v[26:27], v[102:103]
	v_cvt_pk_bf16_f32 v61, v62, v63
	v_pk_mul_f32 v[62:63], v[28:29], v[104:105]
	v_pk_fma_f32 v[58:59], v[78:79], v[58:59], v[64:65]
	v_pk_fma_f32 v[38:39], v[80:81], v[38:39], v[62:63]
	v_pk_fma_f32 v[48:49], v[74:75], v[48:49], v[58:59]
	v_pk_fma_f32 v[36:37], v[76:77], v[36:37], v[38:39]
	v_pk_fma_f32 v[46:47], v[70:71], v[46:47], v[82:83]
	v_mul_f32_e32 v38, 0xbfb8aa3b, v36
	v_mul_f32_e32 v39, 0xbfb8aa3b, v37
	v_exp_f32_e32 v38, v38
	v_exp_f32_e32 v39, v39
	v_mul_f32_e32 v130, 0xbfb8aa3b, v88
	v_pk_fma_f32 v[84:85], v[106:107], v[84:85], v[86:87]
	v_mul_f32_e32 v86, 0xbfb8aa3b, v89
	v_mul_f32_e32 v58, 0xbfb8aa3b, v48
	v_pk_fma_f32 v[44:45], v[66:67], v[44:45], v[46:47]
	v_mul_f32_e32 v46, 0xbfb8aa3b, v49
	v_add_f32_e32 v38, 1.0, v38
	v_add_f32_e32 v39, 1.0, v39
	v_exp_f32_e32 v130, v130
	v_exp_f32_e32 v86, v86
	v_exp_f32_e32 v58, v58
	v_exp_f32_e32 v46, v46
	v_rcp_f32_e32 v38, v38
	v_rcp_f32_e32 v39, v39
	v_pk_mul_f32 v[64:65], v[20:21], v[92:93]
	v_add_f32_e32 v130, 1.0, v130
	v_pk_fma_f32 v[42:43], v[72:73], v[42:43], v[64:65]
	v_add_f32_e32 v86, 1.0, v86
	v_add_f32_e32 v58, 1.0, v58
	v_add_f32_e32 v46, 1.0, v46
	v_pk_fma_f32 v[40:41], v[68:69], v[40:41], v[42:43]
	v_pk_mul_f32 v[36:37], v[36:37], v[38:39]
	v_rcp_f32_e32 v130, v130
	v_rcp_f32_e32 v131, v86
	v_rcp_f32_e32 v58, v58
	v_rcp_f32_e32 v59, v46
	v_pk_mul_f32 v[36:37], v[36:37], v[40:41]
	s_movk_i32 s18, 0x1600
	v_cvt_pk_bf16_f32 v63, v36, v37
	v_mov_b64_e32 v[36:37], s[52:53]
	v_mad_u64_u32 v[36:37], s[8:9], v34, s18, v[36:37]
	v_mov_b32_e32 v34, v37
	v_pk_mul_f32 v[86:87], v[88:89], v[130:131]
	v_pk_mul_f32 v[46:47], v[48:49], v[58:59]
	v_mad_u64_u32 v[34:35], s[8:9], v35, s18, v[34:35]
	v_pk_mul_f32 v[84:85], v[86:87], v[84:85]
	v_pk_mul_f32 v[44:45], v[46:47], v[44:45]
	v_mov_b32_e32 v37, v34
	v_cvt_pk_bf16_f32 v60, v84, v85
	v_cvt_pk_bf16_f32 v62, v44, v45
	v_lshl_add_u64 v[34:35], v[216:217], 1, v[36:37]
	global_store_dwordx4 v[34:35], v[60:63], off
.LBB0_146:
	s_or_b64 exec, exec, s[30:31]
	v_pk_mul_f32 v[16:17], v[16:17], v[198:199] op_sel_hi:[1,0]
	v_pk_mul_f32 v[14:15], v[14:15], v[198:199] op_sel_hi:[1,0]
	v_pk_mul_f32 v[8:9], v[8:9], v[198:199] op_sel_hi:[1,0]
	v_pk_mul_f32 v[6:7], v[6:7], v[198:199] op_sel_hi:[1,0]
	v_pk_mul_f32 v[4:5], v[4:5], v[198:199] op_sel_hi:[1,0]
	v_cndmask_b32_e64 v34, v14, v30, s[42:43]
	v_cndmask_b32_e64 v30, v14, v30, s[40:41]
	v_cndmask_b32_e64 v35, v15, v31, s[42:43]
	v_cndmask_b32_e64 v31, v15, v31, s[40:41]
	v_cndmask_b32_e64 v36, v16, v32, s[42:43]
	v_cndmask_b32_e64 v32, v16, v32, s[40:41]
	v_pk_mul_f32 v[12:13], v[12:13], v[198:199] op_sel_hi:[1,0]
	v_pk_mul_f32 v[10:11], v[10:11], v[198:199] op_sel_hi:[1,0]
	v_cndmask_b32_e64 v37, v17, v33, s[42:43]
	v_cndmask_b32_e64 v33, v17, v33, s[40:41]
	v_mov_b32_dpp v44, v34 row_ror:1 row_mask:0xf bank_mask:0xf bound_ctrl:1
	v_mov_b32_dpp v42, v30 row_ror:2 row_mask:0xf bank_mask:0xf bound_ctrl:1
	v_mov_b32_dpp v43, v31 row_ror:2 row_mask:0xf bank_mask:0xf bound_ctrl:1
	v_mov_b32_dpp v34, v32 row_ror:2 row_mask:0xf bank_mask:0xf bound_ctrl:1
	v_cndmask_b32_e64 v30, v6, v22, s[42:43]
	v_cndmask_b32_e64 v22, v6, v22, s[40:41]
	v_cndmask_b32_e64 v31, v7, v23, s[42:43]
	v_cndmask_b32_e64 v32, v8, v24, s[42:43]
	v_cndmask_b32_e64 v24, v8, v24, s[40:41]
	v_cndmask_b32_e64 v58, v4, v20, s[42:43]
	v_pk_mul_f32 v[2:3], v[2:3], v[198:199] op_sel_hi:[1,0]
	v_mov_b32_dpp v45, v35 row_ror:1 row_mask:0xf bank_mask:0xf bound_ctrl:1
	v_mov_b32_dpp v35, v33 row_ror:2 row_mask:0xf bank_mask:0xf bound_ctrl:1
	v_cndmask_b32_e64 v23, v7, v23, s[40:41]
	v_cndmask_b32_e64 v33, v9, v25, s[42:43]
	v_cndmask_b32_e64 v25, v9, v25, s[40:41]
	v_mov_b32_dpp v48, v30 row_ror:1 row_mask:0xf bank_mask:0xf bound_ctrl:1
	v_mov_b32_dpp v46, v22 row_ror:2 row_mask:0xf bank_mask:0xf bound_ctrl:1
	v_mov_b32_dpp v49, v31 row_ror:1 row_mask:0xf bank_mask:0xf bound_ctrl:1
	v_mov_b32_dpp v38, v24 row_ror:2 row_mask:0xf bank_mask:0xf bound_ctrl:1
	v_cndmask_b32_e64 v22, v10, v26, s[42:43]
	v_cndmask_b32_e64 v24, v11, v27, s[42:43]
	v_cndmask_b32_e64 v30, v12, v28, s[42:43]
	v_cndmask_b32_e64 v31, v12, v28, s[40:41]
	v_cndmask_b32_e64 v59, v4, v20, s[40:41]
	v_mov_b32_dpp v20, v58 row_ror:1 row_mask:0xf bank_mask:0xf bound_ctrl:1
; __device__ __forceinline__ unsigned pk2(float lo, float hi) { f32x2 v = {lo, hi}; bf16x2_t b = __builtin_convertvector(v, bf16x2_t); return __builtin_bit_cast(unsigned, b); }
; __device__ __forceinline__ float sigmoidf_(float z) { return __builtin_amdgcn_rcpf(1.f + __builtin_amdgcn_exp2f(-z * LOG2E)); }
; __device__ __forceinline__ float dpp_ror1(float v) { return __builtin_bit_cast(float, __builtin_amdgcn_mov_dpp(__builtin_bit_cast(int, v), 0x121, 0xf, 0xf, true)); }
; __device__ __forceinline__ float dpp_ror2(float v) { return __builtin_bit_cast(float, __builtin_amdgcn_mov_dpp(__builtin_bit_cast(int, v), 0x122, 0xf, 0xf, true)); }
;     __device__ __forceinline__ void operator()(AccT& acc, const Unit& u, int wr, int wc, int fr, int fq, LAS unsigned char* ldsx) const {
;     ...
;             for (int m = 0; m < 4; ++m) {
;                 u32x4 w;
; #pragma unroll
;                 for (int n = 0; n < 2; ++n) {
;                     const f32x4 cg = acc[ai][0][m][n], cv = acc[ai][1][m][n]; f32x4 o;
;                     float og[4];
;                     { float s1[4], s2[4];
; #pragma unroll
;                       for (int i = 0; i < 4; ++i) { s1[i] = hi1 ? pg[n][i] : cg[i]; s2[i] = hi2 ? pg[n][i] : cg[i]; }
; #pragma unroll
;                       for (int i = 0; i < 4; ++i) { s1[i] = dpp_ror1(s1[i]); s2[i] = dpp_ror2(s2[i]); }
; #pragma unroll
;                       for (int i = 0; i < 4; ++i) og[i] = wg[n][2][i] * cg[i] + wg[n][1][i] * s1[i] + wg[n][0][i] * s2[i]; }
;                     { float s1[4], s2[4];
; #pragma unroll
;                       for (int i = 0; i < 4; ++i) { s1[i] = hi1 ? pv[n][i] : cv[i]; s2[i] = hi2 ? pv[n][i] : cv[i]; }
; #pragma unroll
;                       for (int i = 0; i < 4; ++i) { s1[i] = dpp_ror1(s1[i]); s2[i] = dpp_ror2(s2[i]); }
; #pragma unroll
;                       for (int i = 0; i < 4; ++i) { const float ov = wv[n][2][i] * cv[i] + wv[n][1][i] * s1[i] + wv[n][0][i] * s2[i]; o[i] = og[i] * sigmoidf_(og[i]) * ov; } }
;                     w[2 * n] = pk2(o[0], o[1]); w[2 * n + 1] = pk2(o[2], o[3]);
;                     pg[n] = cg; pv[n] = cv;
;                 }
;                 const bool st = u.sp ? ((m & 1) != 0) : (ai * 128 + wr * 64 + m * 16 + fr >= 2);
;                 if (st) *(u32x4*)(act + tok_row(u, ai, wr, m, fr) * DFF + ch) = w;
	v_add_u32_e32 v58, 0xa0, v204
	v_mov_b32_dpp v47, v23 row_ror:2 row_mask:0xf bank_mask:0xf bound_ctrl:1
	v_mov_b32_dpp v40, v32 row_ror:1 row_mask:0xf bank_mask:0xf bound_ctrl:1
	v_mov_b32_dpp v41, v33 row_ror:1 row_mask:0xf bank_mask:0xf bound_ctrl:1
	v_mov_b32_dpp v39, v25 row_ror:2 row_mask:0xf bank_mask:0xf bound_ctrl:1
	v_cndmask_b32_e64 v23, v10, v26, s[40:41]
	v_cndmask_b32_e64 v25, v11, v27, s[40:41]
	v_cndmask_b32_e64 v32, v13, v29, s[42:43]
	v_cndmask_b32_e64 v33, v13, v29, s[40:41]
	v_mov_b32_dpp v28, v22 row_ror:1 row_mask:0xf bank_mask:0xf bound_ctrl:1
	v_mov_b32_dpp v29, v24 row_ror:1 row_mask:0xf bank_mask:0xf bound_ctrl:1
	v_mov_b32_dpp v24, v30 row_ror:1 row_mask:0xf bank_mask:0xf bound_ctrl:1
	v_mov_b32_dpp v22, v31 row_ror:2 row_mask:0xf bank_mask:0xf bound_ctrl:1
	v_cndmask_b32_e64 v30, v2, v18, s[42:43]
	v_cndmask_b32_e64 v18, v2, v18, s[40:41]
	v_cndmask_b32_e64 v31, v3, v19, s[42:43]
	v_cndmask_b32_e64 v19, v3, v19, s[40:41]
	v_cndmask_b32_e64 v60, v5, v21, s[42:43]
	v_cndmask_b32_e64 v61, v5, v21, s[40:41]
	v_cmp_lt_i32_e32 vcc, 1, v58
	v_mov_b32_dpp v36, v36 row_ror:1 row_mask:0xf bank_mask:0xf bound_ctrl:1
	v_mov_b32_dpp v37, v37 row_ror:1 row_mask:0xf bank_mask:0xf bound_ctrl:1
	v_mov_b32_dpp v26, v23 row_ror:2 row_mask:0xf bank_mask:0xf bound_ctrl:1
	v_mov_b32_dpp v27, v25 row_ror:2 row_mask:0xf bank_mask:0xf bound_ctrl:1
	v_mov_b32_dpp v25, v32 row_ror:1 row_mask:0xf bank_mask:0xf bound_ctrl:1
	v_mov_b32_dpp v23, v33 row_ror:2 row_mask:0xf bank_mask:0xf bound_ctrl:1
	v_mov_b32_dpp v32, v30 row_ror:1 row_mask:0xf bank_mask:0xf bound_ctrl:1
	v_mov_b32_dpp v30, v18 row_ror:2 row_mask:0xf bank_mask:0xf bound_ctrl:1
	v_mov_b32_dpp v33, v31 row_ror:1 row_mask:0xf bank_mask:0xf bound_ctrl:1
	v_mov_b32_dpp v31, v19 row_ror:2 row_mask:0xf bank_mask:0xf bound_ctrl:1
	v_mov_b32_dpp v18, v59 row_ror:2 row_mask:0xf bank_mask:0xf bound_ctrl:1
	v_mov_b32_dpp v21, v60 row_ror:1 row_mask:0xf bank_mask:0xf bound_ctrl:1
	v_mov_b32_dpp v19, v61 row_ror:2 row_mask:0xf bank_mask:0xf bound_ctrl:1
	s_and_b64 s[16:17], s[16:17], vcc
	s_and_saveexec_b64 s[8:9], s[16:17]
	s_cbranch_execz .LBB0_148
	v_pk_mul_f32 v[60:61], v[14:15], v[126:127]
	v_pk_mul_f32 v[62:63], v[16:17], v[128:129]
	v_pk_fma_f32 v[44:45], v[118:119], v[44:45], v[60:61]
	v_pk_fma_f32 v[36:37], v[120:121], v[36:37], v[62:63]
	v_pk_fma_f32 v[42:43], v[114:115], v[42:43], v[44:45]
	v_pk_fma_f32 v[36:37], v[116:117], v[34:35], v[36:37]
	v_mul_f32_e32 v44, 0xbfb8aa3b, v42
	v_exp_f32_e32 v60, v44
	v_mul_f32_e32 v44, 0xbfb8aa3b, v43
	v_exp_f32_e32 v61, v44
	v_pk_mul_f32 v[44:45], v[6:7], v[122:123]
	v_add_f32_e32 v60, 1.0, v60
	v_pk_fma_f32 v[44:45], v[110:111], v[48:49], v[44:45]
	v_add_f32_e32 v61, 1.0, v61
	v_mul_f32_e32 v34, 0xbfb8aa3b, v36
	v_rcp_f32_e32 v60, v60
	v_rcp_f32_e32 v61, v61
	v_pk_fma_f32 v[44:45], v[106:107], v[46:47], v[44:45]
	v_exp_f32_e32 v46, v34
	v_mul_f32_e32 v34, 0xbfb8aa3b, v37
	v_exp_f32_e32 v47, v34
	v_pk_mul_f32 v[42:43], v[42:43], v[60:61]
	v_pk_mul_f32 v[58:59], v[8:9], v[124:125]
	v_pk_mul_f32 v[34:35], v[42:43], v[44:45]
	v_add_f32_e32 v42, 1.0, v46
	v_add_f32_e32 v43, 1.0, v47
	v_rcp_f32_e32 v42, v42
	v_rcp_f32_e32 v43, v43
	v_pk_fma_f32 v[40:41], v[112:113], v[40:41], v[58:59]
	v_cvt_pk_bf16_f32 v34, v34, v35
	v_pk_fma_f32 v[38:39], v[108:109], v[38:39], v[40:41]
	v_pk_mul_f32 v[36:37], v[36:37], v[42:43]
	v_pk_mul_f32 v[40:41], v[12:13], v[104:105]
	v_pk_mul_f32 v[36:37], v[36:37], v[38:39]
	v_pk_fma_f32 v[24:25], v[80:81], v[24:25], v[40:41]
	v_cvt_pk_bf16_f32 v35, v36, v37
	v_pk_mul_f32 v[36:37], v[10:11], v[102:103]
	v_pk_fma_f32 v[22:23], v[76:77], v[22:23], v[24:25]
	v_pk_fma_f32 v[28:29], v[78:79], v[28:29], v[36:37]
	v_mul_f32_e32 v24, 0xbfb8aa3b, v22
	v_pk_fma_f32 v[26:27], v[74:75], v[26:27], v[28:29]
	v_pk_mul_f32 v[38:39], v[4:5], v[92:93]
	v_mul_f32_e32 v28, 0xbfb8aa3b, v26
	v_exp_f32_e32 v36, v28
	v_mul_f32_e32 v28, 0xbfb8aa3b, v27
	v_exp_f32_e32 v37, v28
	v_pk_mul_f32 v[28:29], v[2:3], v[90:91]
	v_add_f32_e32 v36, 1.0, v36
	v_pk_fma_f32 v[28:29], v[70:71], v[32:33], v[28:29]
	v_add_f32_e32 v37, 1.0, v37
	v_rcp_f32_e32 v36, v36
	v_rcp_f32_e32 v37, v37
	v_pk_fma_f32 v[28:29], v[66:67], v[30:31], v[28:29]
	v_exp_f32_e32 v30, v24
	v_mul_f32_e32 v24, 0xbfb8aa3b, v23
	v_exp_f32_e32 v31, v24
	v_pk_mul_f32 v[26:27], v[26:27], v[36:37]
	v_pk_fma_f32 v[20:21], v[72:73], v[20:21], v[38:39]
	v_pk_mul_f32 v[24:25], v[26:27], v[28:29]
	v_add_f32_e32 v26, 1.0, v30
	v_add_f32_e32 v27, 1.0, v31
	v_rcp_f32_e32 v26, v26
	v_rcp_f32_e32 v27, v27
	v_pk_fma_f32 v[18:19], v[68:69], v[18:19], v[20:21]
	v_mov_b32_e32 v215, v1
	s_movk_i32 s18, 0x1600
	v_pk_mul_f32 v[20:21], v[22:23], v[26:27]
	v_cmp_lt_i32_e32 vcc, -1, v214
	v_pk_mul_f32 v[18:19], v[20:21], v[18:19]
	v_cvt_pk_bf16_f32 v36, v24, v25
	v_cvt_pk_bf16_f32 v37, v18, v19
	v_lshl_add_u64 v[18:19], s[64:65], 0, v[214:215]
	v_mad_u64_u32 v[20:21], s[16:17], v18, s18, 0
	v_mad_i32_i24 v19, v19, s18, v21
	v_mov_b32_e32 v18, 0xffffea00
	v_cndmask_b32_e32 v18, v18, v20, vcc
	v_cndmask_b32_e32 v19, -1, v19, vcc
	v_lshl_add_u64 v[18:19], s[52:53], 0, v[18:19]
	v_lshl_add_u64 v[18:19], v[216:217], 1, v[18:19]
	global_store_dwordx4 v[18:19], v[34:37], off

; __device__ __forceinline__ unsigned pk2(float lo, float hi) { f32x2 v = {lo, hi}; bf16x2_t b = __builtin_convertvector(v, bf16x2_t); return __builtin_bit_cast(unsigned, b); }
; __device__ __forceinline__ float sigmoidf_(float z) { return __builtin_amdgcn_rcpf(1.f + __builtin_amdgcn_exp2f(-z * LOG2E)); }
; __device__ __forceinline__ float dpp_ror1(float v) { return __builtin_bit_cast(float, __builtin_amdgcn_mov_dpp(__builtin_bit_cast(int, v), 0x121, 0xf, 0xf, true)); }
; __device__ __forceinline__ float dpp_ror2(float v) { return __builtin_bit_cast(float, __builtin_amdgcn_mov_dpp(__builtin_bit_cast(int, v), 0x122, 0xf, 0xf, true)); }
;     __device__ __forceinline__ void operator()(AccT& acc, const Unit& u, int wr, int wc, int fr, int fq, LAS unsigned char* ldsx) const {
;     ...
;                       for (int i = 0; i < 4; ++i) og[i] = wg[n][2][i] * cg[i] + wg[n][1][i] * s1[i] + wg[n][0][i] * s2[i]; }
;                     { float s1[4], s2[4];
; #pragma unroll
;                       for (int i = 0; i < 4; ++i) { s1[i] = hi1 ? pv[n][i] : cv[i]; s2[i] = hi2 ? pv[n][i] : cv[i]; }
; #pragma unroll
;                       for (int i = 0; i < 4; ++i) { s1[i] = dpp_ror1(s1[i]); s2[i] = dpp_ror2(s2[i]); }
; #pragma unroll
;                       for (int i = 0; i < 4; ++i) { const float ov = wv[n][2][i] * cv[i] + wv[n][1][i] * s1[i] + wv[n][0][i] * s2[i]; o[i] = og[i] * sigmoidf_(og[i]) * ov; } }
;                     w[2 * n] = pk2(o[0], o[1]); w[2 * n + 1] = pk2(o[2], o[3]);
;                     pg[n] = cg; pv[n] = cv;
;                 }
;                 const bool st = u.sp ? ((m & 1) != 0) : (ai * 128 + wr * 64 + m * 16 + fr >= 2);
;                 if (st) *(u32x4*)(act + tok_row(u, ai, wr, m, fr) * DFF + ch) = w;
.LBB0_153:
	v_pk_mul_f32 v[36:37], v[94:95], v[126:127]
	v_pk_mul_f32 v[40:41], v[98:99], v[122:123]
	v_pk_fma_f32 v[34:35], v[118:119], v[34:35], v[36:37]
	v_pk_fma_f32 v[30:31], v[110:111], v[30:31], v[40:41]
	v_pk_fma_f32 v[32:33], v[114:115], v[32:33], v[34:35]
	v_pk_mul_f32 v[34:35], v[96:97], v[128:129]
	v_mul_f32_e32 v0, 0xbfb8aa3b, v32
	v_exp_f32_e32 v0, v0
	v_mul_f32_e32 v39, 0xbfb8aa3b, v33
	v_pk_fma_f32 v[26:27], v[120:121], v[26:27], v[34:35]
	v_pk_fma_f32 v[28:29], v[106:107], v[28:29], v[30:31]
	v_add_f32_e32 v0, 1.0, v0
	v_rcp_f32_e32 v38, v0
	v_exp_f32_e32 v0, v39
	v_pk_fma_f32 v[24:25], v[116:117], v[24:25], v[26:27]
	v_pk_mul_f32 v[36:37], v[100:101], v[124:125]
	v_mul_f32_e32 v26, 0xbfb8aa3b, v25
	v_add_f32_e32 v0, 1.0, v0
	v_rcp_f32_e32 v39, v0
	v_mul_f32_e32 v0, 0xbfb8aa3b, v24
	v_exp_f32_e32 v0, v0
	v_exp_f32_e32 v31, v26
	v_pk_fma_f32 v[22:23], v[112:113], v[22:23], v[36:37]
	v_pk_mul_f32 v[26:27], v[32:33], v[38:39]
	v_add_f32_e32 v0, 1.0, v0
	v_rcp_f32_e32 v30, v0
	v_add_f32_e32 v0, 1.0, v31
	v_rcp_f32_e32 v31, v0
	v_pk_fma_f32 v[20:21], v[108:109], v[20:21], v[22:23]
	v_pk_mul_f32 v[26:27], v[26:27], v[28:29]
	s_movk_i32 s8, 0x1600
	v_pk_mul_f32 v[22:23], v[24:25], v[30:31]
	v_pk_mul_f32 v[24:25], v[56:57], v[92:93]
	v_pk_mul_f32 v[20:21], v[22:23], v[20:21]
	v_pk_mul_f32 v[22:23], v[50:51], v[102:103]
	v_pk_fma_f32 v[4:5], v[72:73], v[4:5], v[24:25]
	v_pk_fma_f32 v[18:19], v[78:79], v[18:19], v[22:23]
	v_pk_fma_f32 v[2:3], v[68:69], v[2:3], v[4:5]
	v_pk_fma_f32 v[18:19], v[74:75], v[16:17], v[18:19]
	v_cvt_pk_bf16_f32 v17, v20, v21
	v_mul_f32_e32 v0, 0xbfb8aa3b, v18
	v_exp_f32_e32 v0, v0
	v_pk_mul_f32 v[20:21], v[52:53], v[104:105]
	v_cvt_pk_bf16_f32 v16, v26, v27
	v_pk_fma_f32 v[8:9], v[80:81], v[8:9], v[20:21]
	v_add_f32_e32 v0, 1.0, v0
	v_rcp_f32_e32 v22, v0
	v_mul_f32_e32 v0, 0xbfb8aa3b, v19
	v_exp_f32_e32 v0, v0
	v_pk_fma_f32 v[6:7], v[76:77], v[6:7], v[8:9]
	v_pk_mul_f32 v[26:27], v[54:55], v[90:91]
	v_mul_f32_e32 v8, 0xbfb8aa3b, v7
	v_add_f32_e32 v0, 1.0, v0
	v_rcp_f32_e32 v23, v0
	v_mul_f32_e32 v0, 0xbfb8aa3b, v6
	v_pk_fma_f32 v[14:15], v[70:71], v[14:15], v[26:27]
	v_exp_f32_e32 v0, v0
	v_pk_fma_f32 v[12:13], v[66:67], v[12:13], v[14:15]
	v_exp_f32_e32 v15, v8
	v_pk_mul_f32 v[8:9], v[18:19], v[22:23]
	v_add_f32_e32 v0, 1.0, v0
	v_rcp_f32_e32 v14, v0
	v_add_f32_e32 v0, 1.0, v15
	v_rcp_f32_e32 v15, v0
	v_pk_mul_f32 v[8:9], v[8:9], v[12:13]
	v_pk_mul_f32 v[4:5], v[6:7], v[14:15]
	s_nop 0
	v_pk_mul_f32 v[2:3], v[4:5], v[2:3]
	v_cvt_pk_bf16_f32 v18, v8, v9
	v_cvt_pk_bf16_f32 v19, v2, v3
	v_mov_b64_e32 v[2:3], s[52:53]
	v_mad_u64_u32 v[2:3], s[0:1], v10, s8, v[2:3]
	v_mov_b32_e32 v0, v3
	v_mad_u64_u32 v[4:5], s[0:1], v11, s8, v[0:1]
	v_mov_b32_e32 v3, v4
	v_lshl_add_u64 v[2:3], v[216:217], 1, v[2:3]
	global_store_dwordx4 v[2:3], v[16:19], off
